# qf + differential-attention odd-unit epilogue: the wait before the staging barrier leaves the 8 prefetched map-0 row loads in flight (vmcnt(8) instead of vmcnt(0))
# speedup vs baseline: 1.0009x; 1.0001x over previous
.Ldat_nopf:
	v_mov_b32_e32 v0, v173
	s_nop 1
	v_permlane32_swap_b32_e32 v173, v0
	v_add_f32_e32 v0, v173, v0
	v_rcp_f32_e32 v0, v0
	s_cmp_eq_u32 s49, 0
	s_cselect_b64 s[6:7], -1, 0
	s_add_u32 s3, s84, s51
	s_addc_u32 s5, s85, 0
	s_and_b64 s[6:7], s[6:7], exec
	s_mulk_i32 s48, 0x2200
	v_pk_mul_f32 v[2:3], v[52:53], v[0:1] op_sel_hi:[1,0]
	v_pk_mul_f32 v[52:53], v[54:55], v[0:1] op_sel_hi:[1,0]
	s_cselect_b32 s5, s5, s50
	s_cselect_b32 s24, s3, s45
	s_cselect_b32 s3, s39, 0xc00
	s_add_i32 s25, s48, 0
	v_cvt_pk_bf16_f32 v2, v2, v3
	v_cvt_pk_bf16_f32 v3, v52, v53
	v_pk_mul_f32 v[52:53], v[56:57], v[0:1] op_sel_hi:[1,0]
	v_pk_mul_f32 v[54:55], v[58:59], v[0:1] op_sel_hi:[1,0]
	v_add3_u32 v68, s25, v193, v188
	v_cvt_pk_bf16_f32 v52, v52, v53
	v_cvt_pk_bf16_f32 v53, v54, v55
	s_waitcnt lgkmcnt(0)
	s_cmp_lg_u32 s49, 0
	s_cbranch_scc1 .Ldat_w8
	s_waitcnt vmcnt(0)
.Ldat_w8:
	s_waitcnt vmcnt(8)
	s_barrier
	ds_write2_b64 v68, v[2:3], v[52:53] offset1:2
	v_pk_mul_f32 v[2:3], v[60:61], v[0:1] op_sel_hi:[1,0]
	v_pk_mul_f32 v[52:53], v[62:63], v[0:1] op_sel_hi:[1,0]
	v_cvt_pk_bf16_f32 v2, v2, v3
	v_cvt_pk_bf16_f32 v3, v52, v53
	v_pk_mul_f32 v[52:53], v[64:65], v[0:1] op_sel_hi:[1,0]
	v_pk_mul_f32 v[54:55], v[66:67], v[0:1] op_sel_hi:[1,0]
	v_cvt_pk_bf16_f32 v52, v52, v53
	v_cvt_pk_bf16_f32 v53, v54, v55
	ds_write2_b64 v68, v[2:3], v[52:53] offset0:4 offset1:6
	v_pk_mul_f32 v[2:3], v[36:37], v[0:1] op_sel_hi:[1,0]
	v_pk_mul_f32 v[36:37], v[38:39], v[0:1] op_sel_hi:[1,0]
	v_cvt_pk_bf16_f32 v2, v2, v3
	v_cvt_pk_bf16_f32 v3, v36, v37
	v_pk_mul_f32 v[36:37], v[40:41], v[0:1] op_sel_hi:[1,0]
	v_pk_mul_f32 v[38:39], v[42:43], v[0:1] op_sel_hi:[1,0]
	v_cvt_pk_bf16_f32 v36, v36, v37
	v_cvt_pk_bf16_f32 v37, v38, v39
	ds_write2_b64 v68, v[2:3], v[36:37] offset0:8 offset1:10
	v_pk_mul_f32 v[2:3], v[44:45], v[0:1] op_sel_hi:[1,0]
	v_pk_mul_f32 v[36:37], v[46:47], v[0:1] op_sel_hi:[1,0]
	v_cvt_pk_bf16_f32 v2, v2, v3
	v_cvt_pk_bf16_f32 v3, v36, v37
	v_pk_mul_f32 v[36:37], v[48:49], v[0:1] op_sel_hi:[1,0]
	v_pk_mul_f32 v[38:39], v[50:51], v[0:1] op_sel_hi:[1,0]
	v_cvt_pk_bf16_f32 v36, v36, v37
	v_cvt_pk_bf16_f32 v37, v38, v39
	ds_write2_b64 v68, v[2:3], v[36:37] offset0:12 offset1:14
	v_pk_mul_f32 v[2:3], v[20:21], v[0:1] op_sel_hi:[1,0]
	v_pk_mul_f32 v[20:21], v[22:23], v[0:1] op_sel_hi:[1,0]
	v_cvt_pk_bf16_f32 v2, v2, v3
	v_cvt_pk_bf16_f32 v3, v20, v21
	v_pk_mul_f32 v[20:21], v[24:25], v[0:1] op_sel_hi:[1,0]
	v_pk_mul_f32 v[22:23], v[26:27], v[0:1] op_sel_hi:[1,0]
	v_cvt_pk_bf16_f32 v20, v20, v21
	v_cvt_pk_bf16_f32 v21, v22, v23
	ds_write2_b64 v68, v[2:3], v[20:21] offset0:16 offset1:18
	v_pk_mul_f32 v[2:3], v[28:29], v[0:1] op_sel_hi:[1,0]
	v_pk_mul_f32 v[20:21], v[30:31], v[0:1] op_sel_hi:[1,0]
	v_cvt_pk_bf16_f32 v2, v2, v3
	v_cvt_pk_bf16_f32 v3, v20, v21
	v_pk_mul_f32 v[20:21], v[32:33], v[0:1] op_sel_hi:[1,0]
	v_pk_mul_f32 v[22:23], v[34:35], v[0:1] op_sel_hi:[1,0]
	v_cvt_pk_bf16_f32 v20, v20, v21
	v_cvt_pk_bf16_f32 v21, v22, v23
	ds_write2_b64 v68, v[2:3], v[20:21] offset0:20 offset1:22
	v_pk_mul_f32 v[2:3], v[4:5], v[0:1] op_sel_hi:[1,0]
	v_pk_mul_f32 v[4:5], v[6:7], v[0:1] op_sel_hi:[1,0]
	v_cvt_pk_bf16_f32 v2, v2, v3
	v_cvt_pk_bf16_f32 v3, v4, v5
	v_pk_mul_f32 v[4:5], v[8:9], v[0:1] op_sel_hi:[1,0]
	v_pk_mul_f32 v[6:7], v[10:11], v[0:1] op_sel_hi:[1,0]
	v_cvt_pk_bf16_f32 v4, v4, v5
	v_cvt_pk_bf16_f32 v5, v6, v7
	ds_write2_b64 v68, v[2:3], v[4:5] offset0:24 offset1:26
	v_pk_mul_f32 v[2:3], v[12:13], v[0:1] op_sel_hi:[1,0]
	v_pk_mul_f32 v[4:5], v[14:15], v[0:1] op_sel_hi:[1,0]
	v_cvt_pk_bf16_f32 v2, v2, v3
	v_cvt_pk_bf16_f32 v3, v4, v5
	v_pk_mul_f32 v[4:5], v[16:17], v[0:1] op_sel_hi:[1,0]
	v_pk_mul_f32 v[6:7], v[18:19], v[0:1] op_sel_hi:[1,0]
	v_cvt_pk_bf16_f32 v4, v4, v5
	v_cvt_pk_bf16_f32 v5, v6, v7
	ds_write2_b64 v68, v[2:3], v[4:5] offset0:28 offset1:30
	s_cmp_lg_u32 s49, 0
	s_cbranch_scc1 .Ldat_fuse
	s_mul_i32 s44, s44, s3
	s_mul_hi_u32 s6, s43, s3
	s_waitcnt lgkmcnt(0)
	s_add_i32 s7, s6, s44
	s_mul_i32 s6, s43, s3
	v_add3_u32 v18, s25, v194, v195
	s_lshl_b64 s[6:7], s[6:7], 1
	ds_read_b128 v[2:5], v18
	ds_read_b128 v[6:9], v18 offset:1088
	s_add_u32 s6, s24, s6
	s_addc_u32 s7, s5, s7
	v_mov_b32_e32 v177, v1
	v_mul_u32_u24_e32 v0, s3, v190
	v_lshl_add_u64 v[14:15], s[6:7], 0, v[176:177]
	v_lshlrev_b32_e32 v0, 1, v0
	v_lshl_add_u64 v[10:11], v[14:15], 0, v[0:1]
	s_waitcnt lgkmcnt(1)
	global_store_dwordx4 v[10:11], v[2:5], off
	s_lshl_b32 s6, s3, 3
	s_mov_b32 s7, s4
	ds_read_b128 v[2:5], v18 offset:2176
	v_lshl_add_u64 v[16:17], v[10:11], 0, s[6:7]
	ds_read_b128 v[10:13], v18 offset:3264
	s_lshl_b32 s5, s3, 2
	s_waitcnt lgkmcnt(2)
	global_store_dwordx4 v[16:17], v[6:9], off
	s_add_i32 s40, s40, 1
	s_nop 0
	v_lshl_add_u64 v[6:7], v[16:17], 0, s[6:7]
	s_waitcnt lgkmcnt(1)
	global_store_dwordx4 v[6:7], v[2:5], off
	s_nop 1
	v_lshl_add_u64 v[2:3], v[6:7], 0, s[6:7]
	s_add_i32 s6, s5, s5
	s_waitcnt lgkmcnt(0)
	global_store_dwordx4 v[2:3], v[10:13], off
	ds_read_b128 v[2:5], v18 offset:4352
	ds_read_b128 v[6:9], v18 offset:5440
	s_add_i32 s6, s6, s6
	v_mov_b32_e32 v0, s6
	v_mad_u32_u24 v12, s3, v190, v0
	v_lshlrev_b32_e32 v0, 1, v12
	v_add_u32_e32 v12, s5, v12
	v_lshl_add_u64 v[10:11], v[14:15], 0, v[0:1]
	v_lshlrev_b32_e32 v0, 1, v12
	s_waitcnt lgkmcnt(1)
	global_store_dwordx4 v[10:11], v[2:5], off
	v_lshl_add_u64 v[10:11], v[14:15], 0, v[0:1]
	ds_read_b128 v[2:5], v18 offset:6528
	s_waitcnt lgkmcnt(1)
	global_store_dwordx4 v[10:11], v[6:9], off
	ds_read_b128 v[6:9], v18 offset:7616
	v_add_u32_e32 v0, s5, v12
	v_lshl_add_u64 v[10:11], v[0:1], 1, v[14:15]
	v_add_u32_e32 v0, s5, v0
	s_waitcnt lgkmcnt(1)
	global_store_dwordx4 v[10:11], v[2:5], off
	s_mov_b64 s[6:7], 0
	s_nop 0
	v_lshl_add_u64 v[2:3], v[0:1], 1, v[14:15]
	s_waitcnt lgkmcnt(0)
	global_store_dwordx4 v[2:3], v[6:9], off
